# norm1 row loop: next-row x prefetch issued after this row's gain/scale/shift loads (counted vmcnt waits no longer drain the prefetch)
# speedup vs baseline: 1.0058x; 1.0014x over previous
; __device__ __forceinline__ u32x2 pack4(f32x4 v) { u32x2 w; w.x = cvt_pk_bf16(v[0], v[1]); w.y = cvt_pk_bf16(v[2], v[3]); return w; }
; #define NORM_LOADX(dst, r_) do { const int r__ = (r_); const float* xr_ = r__ < NLAT ? xlat + (size_t)r__ * DM : xctx + (size_t)(r__ - NLAT) * DM; \
;         _Pragma("unroll") for (int j = 0; j < 4; ++j) dst[j] = *(const f32x4*)(xr_ + 4 * lane + 256 * j); } while (0)
; __device__ __forceinline__ void norm_phase(const float* xlat, const float* xctx, const float* gvec, const float* mod, int sh_off, int sc_off, bf16_t* H, int nrows,
;                                            const float* part, const float* pgate, float* xctx_out, int row_lo) {
;     ...
;     for (int row = gw; row < nrows; row += NGW) {
;         const int bb = row < NLAT ? row >> 11 : 8;
;         f32x4 v[4]; float ss = 0.f;
; #pragma unroll
;         for (int j = 0; j < 4; ++j) v[j] = vn[j];
;         if (row + NGW < nrows) NORM_LOADX(vn, row + NGW);
;         const float* mp = mod + bb * 6144;
;         f32x4 gg[4], sc[4], sh[4];
; #pragma unroll
;         for (int j = 0; j < 4; ++j) { const int col = 4 * lane + 256 * j; gg[j] = *(const f32x4*)(gvec + col); sc[j] = *(const f32x4*)(mp + sc_off + col); sh[j] = *(const f32x4*)(mp + sh_off + col); }
;         if (part != nullptr && row >= NLAT) {
; #pragma unroll
;             for (int j = 0; j < 4; ++j) {
;                 const size_t o = (size_t)(row - NLAT) * DM + 4 * lane + 256 * j;
;                 const f32x4 ps = (*(const f32x4*)(part + o) + *(const f32x4*)(part + (size_t)NCTX * DM + o)) + (*(const f32x4*)(part + (size_t)2 * NCTX * DM + o) + *(const f32x4*)(part + (size_t)3 * NCTX * DM + o));
;                 v[j] = v[j] + *(const f32x4*)(pgate + 4 * lane + 256 * j) * ps;
;                 *(f32x4*)(xctx_out + o) = v[j];
;             }
;         }
; #pragma unroll
;         for (int j = 0; j < 4; ++j) ss += (v[j][0] * v[j][0] + v[j][1] * v[j][1]) + (v[j][2] * v[j][2] + v[j][3] * v[j][3]);
;         const float rstd = __builtin_amdgcn_rsqf(wave_sum(ss) * (1.f / DM) + EPSV);
; #pragma unroll
;         for (int j = 0; j < 4; ++j) {
;             const int col = 4 * lane + 256 * j;
;             const f32x4 y = (v[j] * rstd) * gg[j];
;             const f32x4 hv = y * (sc[j] + 1.f) + sh[j];
;             *(u32x2*)(H + (size_t)row * DM + col) = pack4(hv);
;         }
;     }
.LBB0_175:
	s_or_b64 exec, exec, s[0:1]
	v_pk_mul_f32 v[106:107], v[14:15], v[14:15]
	v_pk_mul_f32 v[108:109], v[12:13], v[12:13]
	v_pk_mul_f32 v[96:97], v[10:11], v[10:11]
	v_pk_mul_f32 v[104:105], v[8:9], v[8:9]
	v_pk_mov_b32 v[110:111], v[108:109], v[106:107] op_sel:[1,0]
	v_mov_b32_e32 v109, v107
	v_pk_add_f32 v[106:107], v[110:111], v[108:109]
	v_pk_mov_b32 v[108:109], v[104:105], v[96:97] op_sel:[1,0]
	v_mov_b32_e32 v105, v97
	v_pk_add_f32 v[96:97], v[108:109], v[104:105]
	v_pk_add_f32 v[106:107], v[106:107], v[106:107] op_sel_hi:[0,1]
	v_pk_add_f32 v[96:97], v[96:97], v[96:97] op_sel_hi:[0,1]
	v_mul_f32_e32 v96, v4, v4
	v_pk_fma_f32 v[104:105], v[4:5], v[4:5], v[96:97] op_sel_hi:[1,1,0]
	v_mul_f32_e32 v96, v6, v6
	v_pk_fma_f32 v[108:109], v[6:7], v[6:7], v[96:97] op_sel_hi:[1,1,0]
	v_mul_f32_e32 v104, v0, v0
	v_mul_f32_e32 v108, v1, v1
	v_mul_f32_e32 v106, v2, v2
	v_mul_f32_e32 v96, v3, v3
	v_pk_add_f32 v[104:105], v[104:105], v[108:109]
	v_pk_add_f32 v[96:97], v[106:107], v[96:97]
	s_waitcnt vmcnt(15)
	v_pk_add_f32 v[78:79], v[78:79], 1.0 op_sel_hi:[1,0]
	v_pk_add_f32 v[96:97], v[104:105], v[96:97]
	v_pk_add_f32 v[76:77], v[76:77], 1.0 op_sel_hi:[1,0]
	v_add_f32_e32 v87, v96, v97
	ds_bpermute_b32 v89, v81, v87
	s_and_b64 s[0:1], exec, vcc
	s_or_b64 s[10:11], s[0:1], s[10:11]
	v_readlane_b32 s0, v255, 24
	v_readlane_b32 s1, v255, 25
	s_waitcnt lgkmcnt(0)
	v_add_f32_e32 v87, v87, v89
	ds_bpermute_b32 v89, v98, v87
	v_lshl_add_u64 v[94:95], v[94:95], 0, s[80:81]
	s_waitcnt lgkmcnt(0)
	v_add_f32_e32 v87, v87, v89
	ds_bpermute_b32 v89, v99, v87
	s_waitcnt lgkmcnt(0)
	v_add_f32_e32 v87, v87, v89
	ds_bpermute_b32 v89, v100, v87
	s_waitcnt lgkmcnt(0)
	v_add_f32_e32 v87, v87, v89
	ds_bpermute_b32 v89, v101, v87
	s_waitcnt lgkmcnt(0)
	v_add_f32_e32 v87, v87, v89
	ds_bpermute_b32 v89, v102, v87
	s_waitcnt lgkmcnt(0)
	v_add_f32_e32 v87, v87, v89
	v_fmamk_f32 v87, v87, 0x3a800000, v193
	v_rsq_f32_e32 v96, v87
	s_nop 0
	v_pk_mul_f32 v[14:15], v[14:15], v[96:97] op_sel_hi:[1,0]
	v_pk_mul_f32 v[12:13], v[12:13], v[96:97] op_sel_hi:[1,0]
	s_waitcnt vmcnt(13)
	v_pk_mul_f32 v[14:15], v[70:71], v[14:15]
	v_pk_mul_f32 v[12:13], v[68:69], v[12:13]
	v_pk_mul_f32 v[8:9], v[8:9], v[96:97] op_sel_hi:[1,0]
	v_pk_fma_f32 v[14:15], v[78:79], v[14:15], v[66:67]
	v_pk_fma_f32 v[12:13], v[76:77], v[12:13], v[64:65]
	v_pk_mul_f32 v[10:11], v[10:11], v[96:97] op_sel_hi:[1,0]
	s_waitcnt vmcnt(12)
	v_pk_mul_f32 v[8:9], v[56:57], v[8:9]
	v_cvt_pk_bf16_f32 v12, v12, v13
	v_cvt_pk_bf16_f32 v13, v14, v15
	s_waitcnt vmcnt(5)
	v_pk_add_f32 v[14:15], v[72:73], 1.0 op_sel_hi:[1,0]
	global_store_dwordx2 v[84:85], v[12:13], off
	v_pk_mul_f32 v[10:11], v[58:59], v[10:11]
	v_pk_add_f32 v[12:13], v[74:75], 1.0 op_sel_hi:[1,0]
	v_pk_fma_f32 v[8:9], v[14:15], v[8:9], v[60:61]
	v_pk_fma_f32 v[10:11], v[12:13], v[10:11], v[62:63]
	v_cvt_pk_bf16_f32 v8, v8, v9
	v_pk_mul_f32 v[6:7], v[6:7], v[96:97] op_sel_hi:[1,0]
	v_cvt_pk_bf16_f32 v9, v10, v11
	v_pk_mul_f32 v[4:5], v[4:5], v[96:97] op_sel_hi:[1,0]
	global_store_dwordx2 v[84:85], v[8:9], off offset:512
	v_pk_mul_f32 v[4:5], v[48:49], v[4:5]
	v_pk_mul_f32 v[6:7], v[50:51], v[6:7]
	v_pk_add_f32 v[8:9], v[54:55], 1.0 op_sel_hi:[1,0]
	v_pk_add_f32 v[10:11], v[52:53], 1.0 op_sel_hi:[1,0]
	v_pk_fma_f32 v[6:7], v[8:9], v[6:7], v[46:47]
	v_pk_fma_f32 v[4:5], v[10:11], v[4:5], v[44:45]
	v_pk_mul_f32 v[0:1], v[0:1], v[96:97] op_sel_hi:[1,0]
	v_cvt_pk_bf16_f32 v4, v4, v5
	v_cvt_pk_bf16_f32 v5, v6, v7
	v_pk_mul_f32 v[2:3], v[2:3], v[96:97] op_sel_hi:[1,0]
	v_pk_mul_f32 v[0:1], v[36:37], v[0:1]
	v_pk_add_f32 v[6:7], v[40:41], 1.0 op_sel_hi:[1,0]
	global_store_dwordx2 v[84:85], v[4:5], off offset:1024
	v_pk_mul_f32 v[2:3], v[38:39], v[2:3]
	v_pk_add_f32 v[4:5], v[42:43], 1.0 op_sel_hi:[1,0]
	s_waitcnt vmcnt(7)
	v_pk_fma_f32 v[0:1], v[6:7], v[0:1], v[32:33]
	v_pk_fma_f32 v[2:3], v[4:5], v[2:3], v[34:35]
	v_cvt_pk_bf16_f32 v0, v0, v1
	s_nop 0
	v_cvt_pk_bf16_f32 v1, v2, v3
	global_store_dwordx2 v[84:85], v[0:1], off offset:1536
	s_waitcnt vmcnt(4)
	v_mov_b64_e32 v[12:13], v[16:17]
	v_mov_b64_e32 v[8:9], v[20:21]
	v_mov_b64_e32 v[4:5], v[24:25]
	v_mov_b64_e32 v[0:1], v[28:29]
	v_lshl_add_u64 v[84:85], v[84:85], 0, s[0:1]
	v_mov_b32_e32 v96, v103
	v_mov_b64_e32 v[14:15], v[18:19]
	v_mov_b64_e32 v[10:11], v[22:23]
	v_mov_b64_e32 v[6:7], v[26:27]
	v_mov_b64_e32 v[2:3], v[30:31]
	s_andn2_b64 exec, exec, s[10:11]
	s_cbranch_execz .LBB0_180
.LBB0_176:
	v_add_u32_e32 v103, s80, v96
	v_add_u32_e32 v32, 0x4000, v103
	s_movk_i32 s0, 0x4800
	s_movk_i32 s12, 0x47ff
	v_cmp_gt_i32_e64 s[100:101], s0, v32
	v_mov_b32_e32 v120, v32
	v_cmp_lt_i32_e32 vcc, s12, v32
	v_add_u32_e32 v97, 0x4000, v96
	v_min_i32_e32 v32, 0x4000, v97
	v_ashrrev_i32_e32 v32, 11, v32
	v_mul_i32_i24_e32 v32, 0x1800, v32
	v_ashrrev_i32_e32 v33, 31, v32
	v_lshl_add_u64 v[32:33], v[32:33], 2, s[48:49]
	s_mov_b64 s[0:1], 0x1000
	v_lshl_add_u64 v[34:35], v[32:33], 0, s[0:1]
	v_mov_b32_e32 v87, v161
	v_mov_b32_e32 v89, v161
	v_mov_b32_e32 v91, v161
	v_lshl_add_u64 v[36:37], v[34:35], 0, v[160:161]
	v_lshl_add_u64 v[32:33], v[32:33], 0, v[160:161]
	v_lshl_add_u64 v[72:73], v[34:35], 0, v[86:87]
	v_lshl_add_u64 v[40:41], v[34:35], 0, v[88:89]
	v_lshl_add_u64 v[34:35], v[34:35], 0, v[90:91]
	global_load_dwordx4 v[76:79], v[36:37], off
	global_load_dwordx4 v[64:67], v[32:33], off
	global_load_dwordx4 v[68:71], v[92:93], off
	global_load_dwordx4 v[56:59], v[92:93], off offset:1024
	global_load_dwordx4 v[60:63], v[32:33], off offset:1024
	global_load_dwordx4 v[44:47], v[32:33], off offset:2048
	global_load_dwordx4 v[48:51], v[92:93], off offset:2048
	global_load_dwordx4 v[36:39], v[92:93], off offset:3072
	global_load_dwordx4 v[52:55], v[40:41], off
	s_nop 0
	global_load_dwordx4 v[40:43], v[34:35], off
	s_nop 0
	global_load_dwordx4 v[72:75], v[72:73], off
	s_nop 0
	global_load_dwordx4 v[32:35], v[32:33], off offset:3072
	s_and_saveexec_b64 s[12:13], s[100:101]
	s_cbranch_execz .Ln1_dummy
	v_readlane_b32 s24, v255, 28
	s_movk_i32 s0, 0x4000
	v_readlane_b32 s20, v255, 30
	v_readlane_b32 s25, v255, 29
	v_cmp_gt_i32_e64 s[0:1], s0, v120
	v_mov_b32_e32 v18, s20
	v_mov_b32_e32 v19, s25
	v_readlane_b32 s20, v255, 31
	v_cndmask_b32_e64 v17, 0, v95, s[0:1]
	v_cndmask_b32_e64 v16, v103, v94, s[0:1]
	v_cndmask_b32_e64 v19, v18, v19, s[0:1]
	v_mov_b32_e32 v18, s20
	v_mov_b32_e32 v20, s24
	v_cndmask_b32_e64 v18, v18, v20, s[0:1]
	v_lshlrev_b64 v[16:17], 12, v[16:17]
	v_lshl_add_u64 v[16:17], v[18:19], 0, v[16:17]
	v_lshl_add_u64 v[28:29], v[16:17], 0, v[160:161]
	global_load_dwordx4 v[16:19], v[28:29], off
	global_load_dwordx4 v[20:23], v[28:29], off offset:1024
	global_load_dwordx4 v[24:27], v[28:29], off offset:2048
	s_nop 0
	global_load_dwordx4 v[28:31], v[28:29], off offset:3072
	s_branch .Ln1_join
; #define NORM_LOADX(dst, r_) do { const int r__ = (r_); const float* xr_ = r__ < NLAT ? xlat + (size_t)r__ * DM : xctx + (size_t)(r__ - NLAT) * DM; \
;         _Pragma("unroll") for (int j = 0; j < 4; ++j) dst[j] = *(const f32x4*)(xr_ + 4 * lane + 256 * j); } while (0)
; __device__ __forceinline__ void norm_phase(const float* xlat, const float* xctx, const float* gvec, const float* mod, int sh_off, int sc_off, bf16_t* H, int nrows,
;                                            const float* part, const float* pgate, float* xctx_out, int row_lo) {
;     ...
;         if (row + NGW < nrows) NORM_LOADX(vn, row + NGW);
;     ...
;         if (part != nullptr && row >= NLAT) {
; #pragma unroll
;             for (int j = 0; j < 4; ++j) {
;                 const size_t o = (size_t)(row - NLAT) * DM + 4 * lane + 256 * j;
;                 const f32x4 ps = (*(const f32x4*)(part + o) + *(const f32x4*)(part + (size_t)NCTX * DM + o)) + (*(const f32x4*)(part + (size_t)2 * NCTX * DM + o) + *(const f32x4*)(part + (size_t)3 * NCTX * DM + o));
;                 v[j] = v[j] + *(const f32x4*)(pgate + 4 * lane + 256 * j) * ps;
;                 *(f32x4*)(xctx_out + o) = v[j];
;             }
.Ln1_dummy:
	s_or_b64 exec, exec, s[12:13]
	global_load_dwordx4 v[16:19], v[92:93], off
	global_load_dwordx4 v[20:23], v[92:93], off
	global_load_dwordx4 v[24:27], v[92:93], off
	global_load_dwordx4 v[28:31], v[92:93], off
.Ln1_join:
	s_or_b64 exec, exec, s[12:13]
	s_movk_i32 s0, 0x3fff
	v_cmp_lt_i32_e64 s[0:1], s0, v97
	s_and_b64 s[12:13], s[4:5], s[0:1]
	s_and_saveexec_b64 s[0:1], s[12:13]
	s_cbranch_execz .LBB0_175
	v_mov_b32_e32 v97, v161
	v_lshlrev_b64 v[96:97], 12, v[96:97]
	v_readlane_b32 s12, v253, 18
	v_lshl_or_b32 v96, v80, 2, v96
	v_readlane_b32 s13, v253, 19
	v_lshl_add_u64 v[108:109], s[14:15], 0, v[96:97]
	global_load_dwordx4 v[108:111], v[108:109], off
	v_lshl_add_u64 v[104:105], s[12:13], 0, v[96:97]
	global_load_dwordx4 v[104:107], v[104:105], off
	s_waitcnt vmcnt(0)
	v_pk_add_f32 v[114:115], v[104:105], v[108:109]
	v_lshl_add_u64 v[104:105], s[46:47], 0, v[96:97]
	v_lshl_add_u64 v[108:109], s[66:67], 0, v[96:97]
	v_pk_add_f32 v[112:113], v[106:107], v[110:111]
	global_load_dwordx4 v[104:107], v[104:105], off
	s_nop 0
	global_load_dwordx4 v[108:111], v[108:109], off
	s_waitcnt vmcnt(0)
	v_pk_add_f32 v[106:107], v[106:107], v[110:111]
	v_pk_add_f32 v[104:105], v[104:105], v[108:109]
	v_pk_add_f32 v[108:109], v[112:113], v[106:107]
	v_pk_add_f32 v[110:111], v[114:115], v[104:105]
	global_load_dwordx4 v[104:107], v[82:83], off
	v_or_b32_e32 v112, 0x400, v96
	v_mov_b32_e32 v113, v97
	s_waitcnt vmcnt(0)
	v_pk_fma_f32 v[14:15], v[106:107], v[108:109], v[14:15]
	v_pk_fma_f32 v[12:13], v[104:105], v[110:111], v[12:13]
	v_lshl_add_u64 v[104:105], s[26:27], 0, v[96:97]
	global_store_dwordx4 v[104:105], v[12:15], off
	v_lshl_add_u64 v[104:105], s[12:13], 0, v[112:113]
	v_lshl_add_u64 v[108:109], s[14:15], 0, v[112:113]
	global_load_dwordx4 v[104:107], v[104:105], off
	s_nop 0
	global_load_dwordx4 v[108:111], v[108:109], off
	s_waitcnt vmcnt(0)
	v_pk_add_f32 v[116:117], v[104:105], v[108:109]
	v_lshl_add_u64 v[104:105], s[46:47], 0, v[112:113]
	v_lshl_add_u64 v[108:109], s[66:67], 0, v[112:113]
	v_pk_add_f32 v[114:115], v[106:107], v[110:111]
	global_load_dwordx4 v[104:107], v[104:105], off
	s_nop 0
	global_load_dwordx4 v[108:111], v[108:109], off
	s_waitcnt vmcnt(0)
	v_pk_add_f32 v[106:107], v[106:107], v[110:111]
	v_pk_add_f32 v[104:105], v[104:105], v[108:109]
	v_pk_add_f32 v[108:109], v[114:115], v[106:107]
	v_pk_add_f32 v[110:111], v[116:117], v[104:105]
	global_load_dwordx4 v[104:107], v[82:83], off offset:1024
	s_waitcnt vmcnt(0)
	v_pk_fma_f32 v[10:11], v[106:107], v[108:109], v[10:11]
	v_pk_fma_f32 v[8:9], v[104:105], v[110:111], v[8:9]
	v_lshl_add_u64 v[104:105], s[26:27], 0, v[112:113]
	v_or_b32_e32 v112, 0x800, v96
	global_store_dwordx4 v[104:105], v[8:11], off
	v_lshl_add_u64 v[104:105], s[12:13], 0, v[112:113]
	v_lshl_add_u64 v[108:109], s[14:15], 0, v[112:113]
	global_load_dwordx4 v[104:107], v[104:105], off
	v_or_b32_e32 v96, 0xc00, v96
	global_load_dwordx4 v[108:111], v[108:109], off
	s_waitcnt vmcnt(0)
	v_pk_add_f32 v[116:117], v[104:105], v[108:109]
	v_lshl_add_u64 v[104:105], s[46:47], 0, v[112:113]
	v_lshl_add_u64 v[108:109], s[66:67], 0, v[112:113]
	v_pk_add_f32 v[114:115], v[106:107], v[110:111]
	global_load_dwordx4 v[104:107], v[104:105], off
	s_nop 0
	global_load_dwordx4 v[108:111], v[108:109], off
	s_waitcnt vmcnt(0)
	v_pk_add_f32 v[106:107], v[106:107], v[110:111]
	v_pk_add_f32 v[104:105], v[104:105], v[108:109]
	v_pk_add_f32 v[108:109], v[114:115], v[106:107]
	v_pk_add_f32 v[110:111], v[116:117], v[104:105]
	global_load_dwordx4 v[104:107], v[82:83], off offset:2048
	s_waitcnt vmcnt(0)
	v_pk_fma_f32 v[6:7], v[106:107], v[108:109], v[6:7]
	v_pk_fma_f32 v[4:5], v[104:105], v[110:111], v[4:5]
	v_lshl_add_u64 v[104:105], s[26:27], 0, v[112:113]
	global_store_dwordx4 v[104:105], v[4:7], off
	v_lshl_add_u64 v[104:105], s[12:13], 0, v[96:97]
	v_lshl_add_u64 v[108:109], s[14:15], 0, v[96:97]
	global_load_dwordx4 v[104:107], v[104:105], off
	s_nop 0
	global_load_dwordx4 v[108:111], v[108:109], off
	s_waitcnt vmcnt(0)
	v_pk_add_f32 v[114:115], v[104:105], v[108:109]
	v_lshl_add_u64 v[104:105], s[46:47], 0, v[96:97]
	v_lshl_add_u64 v[108:109], s[66:67], 0, v[96:97]
	v_pk_add_f32 v[112:113], v[106:107], v[110:111]
	global_load_dwordx4 v[104:107], v[104:105], off
	v_lshl_add_u64 v[96:97], s[26:27], 0, v[96:97]
	global_load_dwordx4 v[108:111], v[108:109], off
	s_waitcnt vmcnt(0)
	v_pk_add_f32 v[106:107], v[106:107], v[110:111]
	v_pk_add_f32 v[104:105], v[104:105], v[108:109]
	v_pk_add_f32 v[108:109], v[112:113], v[106:107]
	v_pk_add_f32 v[110:111], v[114:115], v[104:105]
	global_load_dwordx4 v[104:107], v[82:83], off offset:3072
	s_waitcnt vmcnt(0)
	v_pk_fma_f32 v[2:3], v[106:107], v[108:109], v[2:3]
	v_pk_fma_f32 v[0:1], v[104:105], v[110:111], v[0:1]
	global_store_dwordx4 v[96:97], v[0:3], off
	s_branch .LBB0_175
